# attention loop heads: steady state branches straight to the vmcnt(8) rendezvous; late-half exit-path copies moved onto the exit path (5 fewer instrs per late step, 2 per SB step)
# speedup vs baseline: 1.0041x; 1.0014x over previous
.Lsb_b8:
	s_waitcnt vmcnt(8) lgkmcnt(0)
	s_barrier

.Llate_x392:
	v_readfirstlane_b32 s12, v0
	v_readfirstlane_b32 s13, v0
	v_readfirstlane_b32 s14, v0

.LBB0_393:
	s_mov_b64 s[8:9], -1
	s_cmp_eq_u32 s80, -4
	s_cbranch_scc1 .Llate_x392
	s_add_i32 s12, s80, 3
	s_cmp_lt_i32 s12, 2
	s_cbranch_scc0 .Llate_b8
	s_cmp_lg_u32 s80, -2
	s_cbranch_scc0 .LBB0_397
	s_waitcnt vmcnt(0) lgkmcnt(0)
	s_barrier
	s_mov_b64 s[8:9], 0
